# speedup vs baseline: 1.0086x; 1.0041x over previous
; #define LAS __attribute__((address_space(3)))
; __global__ void __launch_bounds__(NTHREADS, 2) fwd_kernel(Args args) {
;     extern __shared__ __attribute__((aligned(16))) unsigned char lds_raw[];
;     LAS unsigned char* lds = (LAS unsigned char*)lds_raw;
;     cg::grid_group grid = cg::this_grid();
;     const int tid = threadIdx.x, lane = tid & 63, wave = __builtin_amdgcn_readfirstlane(tid >> 6);
;     const int nb = gridDim.x, bx = blockIdx.x, gw = bx * NWAVES + wave, NGW = nb * NWAVES, gt = bx * NTHREADS + tid, NT = nb * NTHREADS;
;     const int lo = args.ph_lo, hi = args.ph_hi;
;     ...
;     unsigned* xbw = (unsigned*)(args.ws + WS_END + 1024);
;     volatile LAS unsigned* xbst = (volatile LAS unsigned*)(lds + LDS_BYTES - 32);
;     if (tid == 0) { xbst[0] = 0u; xbst[1] = 0u; }
;     __syncthreads();
_Z10fwd_kernel4Args:
	s_mov_b32 s98, 0
	s_load_dwordx4 s[20:23], s[0:1], 0x100
	s_load_dwordx2 s[40:41], s[0:1], 0x110
	s_load_dword s84, s[0:1], 0x118
	s_add_u32 s4, s0, 0x110
	s_addc_u32 s5, s1, 0
	v_and_b32_e32 v140, 0x3ff, v0
	v_writelane_b32 v232, s4, 0
	v_readfirstlane_b32 s66, v140
	v_cmp_eq_u32_e64 s[88:89], 0, v140
	v_writelane_b32 v232, s5, 1
	s_and_saveexec_b64 s[4:5], s[88:89]
	s_cbranch_execz .LBB0_2
	s_add_i32 s3, 0, 0x23fe0
	v_mov_b32_e32 v1, 0
	v_mov_b32_e32 v2, s3
	s_add_i32 s3, 0, 0x23fe4
	ds_write_b32 v2, v1
	v_mov_b32_e32 v2, s3
	ds_write_b32 v2, v1

; __device__ __forceinline__ void scan_quarter(LAS unsigned char* lds, const ScanConst& C, int m0, int T, int h, int quarter, const float* shift_prev  , const float* S0p  , float* Sout, const float* cWg, const float* cWu, const float* cWd, bf16* cWGU, bf16* cWD, int& conv_next, int conv_stride, int wa ...
;     ...
;             if (conv_pending) { conv_finish(cWg, cWu, cWd, cWGU, cWD, conv_next, cv, cscr, lane); conv_next += conv_stride; conv_pending = false; }
;             if (c + 1 < nch) { PREP_FINISH(c + 1, nxt); if (c + 2 < nch) PREP_LOAD(c + 2); }
.LBB0_820:
	s_andn2_b64 vcc, exec, s[76:77]
	s_mov_b64 s[76:77], 0
	s_cbranch_vccnz .LBB0_834
	s_cmp_lg_u64 s[74:75], 0
	s_cselect_b32 s99, 1, 0
.LBB0_823:
	s_cmpk_gt_u32 s18, 0x7e
	s_cbranch_scc1 .LBB0_828
	s_cmp_eq_u32 s98, 0
	s_cbranch_scc1 .Lpf_wait1_plain
	s_waitcnt vmcnt(33)
	s_branch .Lpf_wait1_done
.Lpf_wait1_plain:
	s_waitcnt vmcnt(1)
.Lpf_wait1_done:
	v_lshlrev_b32_e32 v2, 16, v106
	v_and_b32_e32 v3, 0xffff0000, v106
	v_mul_f32_e32 v2, 0xbfb8aa3b, v2
	v_exp_f32_e32 v160, v2
	v_mul_f32_e32 v2, 0xbfb8aa3b, v3
	v_exp_f32_e32 v161, v2
	v_lshlrev_b32_e32 v2, 16, v82
	v_and_b32_e32 v3, 0xffff0000, v82
	v_lshlrev_b32_e32 v162, 16, v98
	v_and_b32_e32 v163, 0xffff0000, v98
	v_lshlrev_b32_e32 v4, 16, v107
	v_pk_add_f32 v[162:163], v[162:163], v[2:3] neg_lo:[0,1] neg_hi:[0,1]
	v_and_b32_e32 v115, 0xffff0000, v107
	v_pk_fma_f32 v[164:165], v[46:47], v[162:163], v[2:3]
	v_mul_f32_e32 v2, 0xbfb8aa3b, v4
	v_exp_f32_e32 v162, v2
	v_mul_f32_e32 v2, 0xbfb8aa3b, v115
	v_exp_f32_e32 v163, v2
	v_lshlrev_b32_e32 v2, 16, v83
	v_and_b32_e32 v3, 0xffff0000, v83
	v_lshlrev_b32_e32 v168, 16, v99
	v_and_b32_e32 v169, 0xffff0000, v99
	v_lshlrev_b32_e32 v159, 16, v108
	v_pk_add_f32 v[168:169], v[168:169], v[2:3] neg_lo:[0,1] neg_hi:[0,1]
	v_and_b32_e32 v167, 0xffff0000, v108
	v_pk_fma_f32 v[180:181], v[48:49], v[168:169], v[2:3]
	v_mul_f32_e32 v2, 0xbfb8aa3b, v159
	v_and_b32_e32 v177, 0xffff0000, v93
	v_lshlrev_b32_e32 v176, 16, v93
	v_and_b32_e32 v179, 0xffff0000, v105
	v_lshlrev_b32_e32 v178, 16, v105
	v_exp_f32_e32 v168, v2
	v_mul_f32_e32 v2, 0xbfb8aa3b, v167
	v_pk_add_f32 v[178:179], v[178:179], v[176:177] neg_lo:[0,1] neg_hi:[0,1]
	v_exp_f32_e32 v169, v2
	v_lshlrev_b32_e32 v2, 16, v84
	v_and_b32_e32 v3, 0xffff0000, v84
	v_lshlrev_b32_e32 v170, 16, v100
	v_and_b32_e32 v171, 0xffff0000, v100
	v_pk_fma_f32 v[188:189], v[56:57], v[178:179], v[176:177]
	v_lshlrev_b32_e32 v178, 16, v90
	v_and_b32_e32 v179, 0xffff0000, v90
	v_lshlrev_b32_e32 v192, 16, v102
	v_and_b32_e32 v193, 0xffff0000, v102
	v_pk_add_f32 v[170:171], v[170:171], v[2:3] neg_lo:[0,1] neg_hi:[0,1]
	v_pk_add_f32 v[192:193], v[192:193], v[178:179] neg_lo:[0,1] neg_hi:[0,1]
	v_lshlrev_b32_e32 v196, 16, v91
	v_and_b32_e32 v197, 0xffff0000, v91
	v_lshlrev_b32_e32 v198, 16, v103
	v_and_b32_e32 v199, 0xffff0000, v103
	v_lshlrev_b32_e32 v172, 16, v109
	v_pk_fma_f32 v[182:183], v[58:59], v[170:171], v[2:3]
	v_and_b32_e32 v3, 0xffff0000, v92
	v_lshlrev_b32_e32 v2, 16, v92
	v_and_b32_e32 v171, 0xffff0000, v104
	v_lshlrev_b32_e32 v170, 16, v104
	v_pk_fma_f32 v[192:193], v[38:39], v[192:193], v[178:179]
	v_pk_add_f32 v[198:199], v[198:199], v[196:197] neg_lo:[0,1] neg_hi:[0,1]
	v_and_b32_e32 v173, 0xffff0000, v109
	v_pk_add_f32 v[170:171], v[170:171], v[2:3] neg_lo:[0,1] neg_hi:[0,1]
	v_mul_f32_e32 v4, 0xbfb8aa3b, v172
	v_pk_mul_f32 v[194:195], v[62:63], v[192:193]
	v_pk_fma_f32 v[196:197], v[40:41], v[198:199], v[196:197]
	v_pk_fma_f32 v[184:185], v[54:55], v[170:171], v[2:3]
	v_exp_f32_e32 v170, v4
	v_mul_f32_e32 v4, 0xbfb8aa3b, v173
	v_pk_mul_f32 v[178:179], v[194:195], v[194:195]
	v_pk_mul_f32 v[198:199], v[64:65], v[196:197]
	v_exp_f32_e32 v171, v4
	v_pk_mul_f32 v[200:201], v[198:199], v[198:199]
	v_add_f32_e32 v4, v178, v179
	v_pk_mul_f32 v[186:187], v[66:67], v[184:185]
	v_add_f32_e32 v4, v200, v4
	v_pk_mul_f32 v[2:3], v[186:187], v[186:187]
	v_add_f32_e32 v4, v201, v4
	v_pk_mul_f32 v[190:191], v[68:69], v[188:189]
	v_add_f32_e32 v2, v2, v4
	v_pk_mul_f32 v[176:177], v[190:191], v[190:191]
	v_add_f32_e32 v2, v3, v2
	v_add_f32_e32 v2, v176, v2
	v_add_f32_e32 v2, v177, v2
	s_and_b64 s[30:31], s[30:31], exec
	s_cselect_b32 s10, s91, 0
	v_add_f32_dpp v2, v2, v2 quad_perm:[1,0,3,2] row_mask:0xf bank_mask:0xf bound_ctrl:1
	v_lshlrev_b32_e32 v172, 16, v85
	v_and_b32_e32 v173, 0xffff0000, v85
	v_add_f32_dpp v2, v2, v2 quad_perm:[2,3,0,1] row_mask:0xf bank_mask:0xf bound_ctrl:1
	v_lshlrev_b32_e32 v174, 16, v101
	v_and_b32_e32 v175, 0xffff0000, v101
	v_add_f32_dpp v2, v2, v2 row_half_mirror row_mask:0xf bank_mask:0xf bound_ctrl:1
	v_max_f32_e32 v2, 0x179abe15, v2
	v_rsq_f32_e32 v2, v2
	v_pk_add_f32 v[174:175], v[174:175], v[172:173] neg_lo:[0,1] neg_hi:[0,1]
	v_add_u32_e32 v115, s10, v143
	v_pk_fma_f32 v[200:201], v[60:61], v[174:175], v[172:173]
	v_lshl_add_u32 v167, v141, 2, v115
	v_pk_mul_f32 v[172:173], v[194:195], v[2:3] op_sel_hi:[1,0]
	v_pk_mul_f32 v[174:175], v[198:199], v[2:3] op_sel_hi:[1,0]
	v_pk_mul_f32 v[176:177], v[164:165], v[160:161]
	v_pk_mul_f32 v[178:179], v[180:181], v[162:163]
	ds_write_b128 v167, v[172:175]
	ds_write_b128 v167, v[176:179] offset:256
	ds_write_b128 v167, v[160:163] offset:512
	s_cmp_eq_u32 s98, 0
	s_cbranch_scc1 .Lpf_wait0_plain
	s_waitcnt vmcnt(32)
	s_branch .Lpf_wait0_done

.Lpf_wait0_done:
	v_lshlrev_b32_e32 v176, 16, v110
	v_and_b32_e32 v177, 0xffff0000, v110
	v_pk_mul_f32 v[160:161], v[194:195], v[176:177]
	v_pk_mul_f32 v[172:173], v[172:173], v[176:177]
	v_pk_mul_f32 v[162:163], v[164:165], v[160:161]
	v_pk_add_f32 v[160:161], v[176:177], -1.0 op_sel_hi:[1,0]
	v_add_f32_e32 v3, 0, v162
	v_pk_fma_f32 v[160:161], v[70:71], v[160:161], 1.0 op_sel_hi:[1,1,0]
	v_add_f32_e32 v3, v163, v3
	v_pk_mul_f32 v[160:161], v[192:193], v[160:161]
	s_nop 0
	v_pk_mul_f32 v[164:165], v[164:165], v[160:161]
	s_nop 0
	v_add_f32_e32 v4, 0, v164
	v_add_f32_e32 v4, v165, v4
	v_lshlrev_b32_e32 v164, 16, v111
	v_and_b32_e32 v165, 0xffff0000, v111
	v_pk_mul_f32 v[162:163], v[198:199], v[164:165]
	v_pk_mul_f32 v[174:175], v[174:175], v[164:165]
	v_pk_mul_f32 v[178:179], v[180:181], v[162:163]
	v_pk_add_f32 v[162:163], v[164:165], -1.0 op_sel_hi:[1,0]
	v_add_f32_e32 v3, v178, v3
	v_pk_fma_f32 v[162:163], v[72:73], v[162:163], 1.0 op_sel_hi:[1,1,0]
	v_add_f32_e32 v3, v179, v3
	v_pk_mul_f32 v[162:163], v[196:197], v[162:163]
	ds_write_b128 v167, v[172:175] offset:768
	ds_write_b128 v167, v[160:163] offset:1024
	v_pk_mul_f32 v[180:181], v[180:181], v[162:163]
	v_pk_mul_f32 v[162:163], v[186:187], v[2:3] op_sel_hi:[1,0]
	v_pk_mul_f32 v[164:165], v[190:191], v[2:3] op_sel_hi:[1,0]
	v_pk_mul_f32 v[172:173], v[182:183], v[168:169]
	v_pk_mul_f32 v[174:175], v[200:201], v[170:171]
	ds_write_b128 v167, v[162:165] offset:16
	ds_write_b128 v167, v[172:175] offset:272
	ds_write_b128 v167, v[168:171] offset:528
	v_lshlrev_b32_e32 v172, 16, v112
	v_and_b32_e32 v173, 0xffff0000, v112
	v_pk_add_f32 v[168:169], v[172:173], -1.0 op_sel_hi:[1,0]
	v_add_f32_e32 v4, v180, v4
	v_pk_fma_f32 v[168:169], v[74:75], v[168:169], 1.0 op_sel_hi:[1,1,0]
	v_add_f32_e32 v4, v181, v4
	v_pk_mul_f32 v[168:169], v[184:185], v[168:169]
	v_pk_mul_f32 v[160:161], v[186:187], v[172:173]
	v_pk_mul_f32 v[170:171], v[182:183], v[168:169]
	v_lshlrev_b32_e32 v174, 16, v113
	v_add_f32_e32 v4, v170, v4
	v_and_b32_e32 v175, 0xffff0000, v113
	v_pk_mul_f32 v[160:161], v[182:183], v[160:161]
	v_add_f32_e32 v4, v171, v4
	v_pk_add_f32 v[170:171], v[174:175], -1.0 op_sel_hi:[1,0]
	v_add_f32_e32 v3, v160, v3
	v_pk_fma_f32 v[170:171], v[76:77], v[170:171], 1.0 op_sel_hi:[1,1,0]
	v_add_f32_e32 v3, v161, v3
	v_pk_mul_f32 v[160:161], v[190:191], v[174:175]
	v_pk_mul_f32 v[170:171], v[188:189], v[170:171]
	v_pk_mul_f32 v[160:161], v[200:201], v[160:161]
	v_pk_mul_f32 v[176:177], v[200:201], v[170:171]
	v_add_f32_e32 v3, v160, v3
	v_add_f32_e32 v4, v176, v4
	v_add_f32_e32 v3, v161, v3
	v_add_f32_e32 v159, v177, v4
	v_pk_mul_f32 v[162:163], v[162:163], v[172:173]
	v_add_f32_dpp v3, v3, v3 quad_perm:[1,0,3,2] row_mask:0xf bank_mask:0xf bound_ctrl:1
	v_add_f32_dpp v159, v159, v159 quad_perm:[1,0,3,2] row_mask:0xf bank_mask:0xf bound_ctrl:1
	v_pk_mul_f32 v[164:165], v[164:165], v[174:175]
	v_add_f32_dpp v3, v3, v3 quad_perm:[2,3,0,1] row_mask:0xf bank_mask:0xf bound_ctrl:1
	v_add_f32_dpp v159, v159, v159 quad_perm:[2,3,0,1] row_mask:0xf bank_mask:0xf bound_ctrl:1
	ds_write_b128 v167, v[162:165] offset:784
	ds_write_b128 v167, v[168:171] offset:1040
	v_mov_b32_dpp v4, v3 row_half_mirror row_mask:0xf bank_mask:0xf bound_ctrl:1
	v_mov_b32_dpp v160, v159 row_half_mirror row_mask:0xf bank_mask:0xf bound_ctrl:1
	s_and_saveexec_b64 s[30:31], s[8:9]
	s_cbranch_execz .LBB0_826
	v_add_f32_e32 v3, v3, v4
	v_mul_f32_e32 v3, v2, v3
	v_add_f32_e32 v4, v159, v160
	v_and_b32_e32 v160, 0xffff0000, v89
	v_and_b32_e32 v2, 0xffff0000, v97
	v_sub_f32_e32 v2, v2, v160
	v_fmac_f32_e32 v160, v53, v2
	v_lshlrev_b32_e32 v162, 16, v89
	v_lshlrev_b32_e32 v2, 16, v97
	v_sub_f32_e32 v2, v2, v162
	v_fmac_f32_e32 v162, v52, v2
	v_and_b32_e32 v168, 0xffff0000, v88
	v_and_b32_e32 v2, 0xffff0000, v96
	v_sub_f32_e32 v2, v2, v168
	v_fmac_f32_e32 v168, v51, v2
	v_lshlrev_b32_e32 v170, 16, v88
	v_lshlrev_b32_e32 v2, 16, v96
	v_sub_f32_e32 v2, v2, v170
	v_fmac_f32_e32 v170, v50, v2
	v_and_b32_e32 v172, 0xffff0000, v87
	v_and_b32_e32 v2, 0xffff0000, v95
	v_sub_f32_e32 v2, v2, v172
	v_fmac_f32_e32 v172, v45, v2
	v_lshlrev_b32_e32 v174, 16, v87
	v_lshlrev_b32_e32 v2, 16, v95
	v_sub_f32_e32 v2, v2, v174
	v_fmac_f32_e32 v174, v44, v2
	v_and_b32_e32 v176, 0xffff0000, v86
	v_and_b32_e32 v2, 0xffff0000, v94
	v_sub_f32_e32 v2, v2, v176
	v_fmac_f32_e32 v176, v43, v2
	v_lshl_add_u32 v115, v146, 2, v115
	v_mov_b32_e32 v177, v3
	v_mov_b32_e32 v178, v4
	v_mov_b32_e32 v179, v5
	ds_write_b128 v115, v[176:179] offset:1296
	v_mov_b32_e32 v175, v3
	v_mov_b32_e32 v176, v4
	v_mov_b32_e32 v177, v5
	v_lshlrev_b32_e32 v2, 16, v86
	v_lshlrev_b32_e32 v159, 16, v94
	ds_write_b128 v115, v[174:177] offset:1312
	v_mov_b32_e32 v173, v3
	v_mov_b32_e32 v174, v4
	v_mov_b32_e32 v175, v5
	v_sub_f32_e32 v159, v159, v2
	ds_write_b128 v115, v[172:175] offset:1328
	v_mov_b32_e32 v171, v3
	v_mov_b32_e32 v172, v4
	v_mov_b32_e32 v173, v5
	v_mov_b32_e32 v163, v3
	v_mov_b32_e32 v164, v4
	v_mov_b32_e32 v165, v5
	v_fmac_f32_e32 v2, v42, v159
	ds_write_b128 v115, v[170:173] offset:1344
	v_mov_b32_e32 v169, v3
	v_mov_b32_e32 v170, v4
	v_mov_b32_e32 v171, v5
	ds_write_b128 v115, v[162:165] offset:1376
	v_mov_b32_e32 v161, v3
	v_mov_b32_e32 v162, v4
	v_mov_b32_e32 v163, v5
	ds_write_b128 v115, v[2:5] offset:1280
	ds_write_b128 v115, v[168:171] offset:1360
	ds_write_b128 v115, v[160:163] offset:1392

; #define LAS __attribute__((address_space(3)))
; __device__ __forceinline__ unsigned pk2(float lo, float hi) { return pg8::cvt_pk_bf16(lo, hi); }
; __device__ __forceinline__ void conv_finish(const float* cWg, const float* cWu, const float* cWd, bf16* cWGU, bf16* cWD, int it, const float (&v)[32], LAS float* scr, int lane) {
;     const ConvItem c = conv_decode(cWg, cWu, cWd, cWGU, cWD, it);
; #pragma unroll
;     for (int i = 0; i < 32; ++i) { const int kk = 2 * i + (lane >> 5); scr[kk * 33 + (lane & 31)] = v[i]; }
;     asm volatile("s_waitcnt lgkmcnt(0)" ::: "memory");
;     const int cc = lane & 7;
; #pragma unroll
;     for (int j = 0; j < 4; ++j) { const int n = (lane >> 3) + 8 * j; const LAS float* s = scr + (8 * cc) * 33 + n;
;         u32x4 o; o.x = pk2(s[0 * 33], s[1 * 33]); o.y = pk2(s[2 * 33], s[3 * 33]); o.z = pk2(s[4 * 33], s[5 * 33]); o.w = pk2(s[6 * 33], s[7 * 33]);
;         *(u32x4*)(c.WT + (size_t)(c.row_base + n) * c.ldk + c.k0 + 8 * cc) = o; }
;     asm volatile("s_waitcnt lgkmcnt(0)" ::: "memory");
; }
; __device__ __forceinline__ void scan_quarter(LAS unsigned char* lds, const ScanConst& C, int m0, int T, int h, int quarter, const float* shift_prev  , const float* S0p  , float* Sout, const float* cWg, const float* cWu, const float* cWd, bf16* cWGU, bf16* cWD, int& conv_next, int conv_stride, int wa ...
;     ...
;             if (conv_pending) { conv_finish(cWg, cWu, cWd, cWGU, cWD, conv_next, cv, cscr, lane); conv_next += conv_stride; conv_pending = false; }
.LBB0_832:
	s_cmp_eq_u32 s99, 0
	s_cbranch_scc1 .Lconv_no_finish
	s_cmp_lg_u32 s98, 0
	s_cbranch_scc1 .Lconv_keep_pending
	s_waitcnt vmcnt(10)
	s_add_i32 s43, s33, 0xffffea80
	s_add_i32 s74, s33, 0xffffd500
	s_cmpk_lt_u32 s43, 0x1580
	s_cselect_b32 s43, s43, s33
	s_cselect_b32 s75, 0x80, 0
	s_cmpk_lt_i32 s33, 0x2b00
	s_cselect_b32 s76, 0xac, 64
	v_cvt_f32_ubyte0_e32 v2, s76
	v_rcp_iflag_f32_e32 v2, v2
	s_cselect_b32 s43, s43, s74
	s_sub_i32 vcc_lo, 0, s76
	s_abs_i32 s77, s43
	v_mul_f32_e32 v2, 0x4f7ffffe, v2
	v_cvt_u32_f32_e32 v2, v2
	s_ashr_i32 s74, s43, 31
	ds_write2_b32 v151, v6, v7 offset1:66
	ds_write2_b32 v151, v8, v9 offset0:132 offset1:198
	v_lshlrev_b32_e32 v4, 1, v135
	v_readfirstlane_b32 vcc_hi, v2
	s_mul_i32 vcc_lo, vcc_lo, vcc_hi
	s_mul_hi_u32 vcc_lo, vcc_hi, vcc_lo
	s_add_i32 vcc_hi, vcc_hi, vcc_lo
	s_mul_hi_u32 vcc_lo, s77, vcc_hi
	s_mul_i32 vcc_hi, vcc_lo, s76
	s_sub_i32 s77, s77, vcc_hi
	s_add_i32 vcc_hi, vcc_lo, 1
	s_sub_i32 s10, s77, s76
	s_cmp_ge_u32 s77, s76
	s_cselect_b32 s11, vcc_hi, vcc_lo
	s_cselect_b32 s10, s10, s77
	s_add_i32 s77, s11, 1
	s_cmp_ge_u32 s10, s76
	s_cselect_b32 s10, s77, s11
	s_xor_b32 s10, s10, s74
	s_sub_i32 s10, s10, s74
	s_mul_i32 s11, s10, s76
	v_add_u32_e32 v2, 0x400, v151
	s_sub_i32 s11, s43, s11
	ds_write2_b32 v2, v10, v11 offset0:8 offset1:74
	ds_write2_b32 v2, v12, v13 offset0:140 offset1:206
	v_add_u32_e32 v2, 0x800, v151
	s_lshl_b32 s74, s11, 5
	ds_write2_b32 v2, v14, v15 offset0:16 offset1:82
	ds_write2_b32 v2, v16, v17 offset0:148 offset1:214
	v_add_u32_e32 v2, 0xc00, v151
	s_and_b32 s43, s74, 0x60
	s_lshl_b32 s11, s11, 6
	ds_write2_b32 v2, v18, v19 offset0:24 offset1:90
	ds_write2_b32 v2, v20, v21 offset0:156 offset1:222
	v_add_u32_e32 v2, 0x1000, v151
	s_or_b32 s43, s43, s75
	s_and_b32 s11, s11, 0xffffff00
	ds_write2_b32 v2, v22, v23 offset0:32 offset1:98
	ds_write2_b32 v2, v24, v25 offset0:164 offset1:230
	v_add_u32_e32 v2, 0x1400, v151
	s_or_b32 s11, s43, s11
	ds_write2_b32 v2, v26, v27 offset0:40 offset1:106
	ds_write2_b32 v2, v28, v29 offset0:172 offset1:238
	v_add_u32_e32 v2, 0x1800, v151
	s_cmpk_lt_i32 s33, 0x2b00
	ds_write2_b32 v2, v30, v31 offset0:48 offset1:114
	ds_write2_b32 v2, v32, v33 offset0:180 offset1:246
	v_add_u32_e32 v2, 0x1c00, v151
	s_cselect_b32 s43, s94, 0x1580
	s_cselect_b32 s75, s17, s47
	s_cselect_b32 vcc_lo, s16, s46
	s_cselect_b32 s74, s11, s74
	ds_write2_b32 v2, v34, v35 offset0:56 offset1:122
	ds_write2_b32 v2, v36, v37 offset0:188 offset1:254
	s_lshl_b32 s76, s10, 6
	s_waitcnt lgkmcnt(0)
	s_ashr_i32 s77, s76, 31
	s_lshl_b64 s[76:77], s[76:77], 1
	ds_read2_b32 v[160:161], v152 offset1:33
	s_add_u32 s76, vcc_lo, s76
	s_waitcnt lgkmcnt(0)
	v_cvt_pk_bf16_f32 v160, v160, v161
	ds_read2_b32 v[162:163], v152 offset0:66 offset1:99
	s_addc_u32 s77, s75, s77
	s_waitcnt lgkmcnt(0)
	v_cvt_pk_bf16_f32 v161, v162, v163
	ds_read2_b32 v[162:163], v152 offset0:132 offset1:165
	v_lshl_add_u64 v[2:3], s[76:77], 0, v[4:5]
	s_waitcnt lgkmcnt(0)
	v_cvt_pk_bf16_f32 v162, v162, v163
	ds_read2_b32 v[164:165], v152 offset0:198 offset1:231
	v_or_b32_e32 v4, s74, v1
	s_waitcnt lgkmcnt(0)
	v_cvt_pk_bf16_f32 v163, v164, v165
	v_mad_i64_i32 v[164:165], s[76:77], s43, v4, 0
	v_lshl_add_u64 v[164:165], v[164:165], 1, v[2:3]
	global_store_dwordx4 v[164:165], v[160:163], off
	ds_read2_b32 v[160:161], v152 offset0:8 offset1:41
	v_or_b32_e32 v4, s74, v131
	s_waitcnt lgkmcnt(0)
	v_cvt_pk_bf16_f32 v160, v160, v161
	ds_read2_b32 v[162:163], v152 offset0:74 offset1:107
	s_waitcnt lgkmcnt(0)
	v_cvt_pk_bf16_f32 v161, v162, v163
	ds_read2_b32 v[162:163], v152 offset0:140 offset1:173
	s_waitcnt lgkmcnt(0)
	v_cvt_pk_bf16_f32 v162, v162, v163
	ds_read2_b32 v[164:165], v152 offset0:206 offset1:239
	s_waitcnt lgkmcnt(0)
	v_cvt_pk_bf16_f32 v163, v164, v165
	v_mad_i64_i32 v[164:165], s[76:77], s43, v4, 0
	v_lshl_add_u64 v[164:165], v[164:165], 1, v[2:3]
	global_store_dwordx4 v[164:165], v[160:163], off
	ds_read2_b32 v[160:161], v152 offset0:16 offset1:49
	v_or_b32_e32 v4, s74, v132
	s_waitcnt lgkmcnt(0)
	v_cvt_pk_bf16_f32 v160, v160, v161
	ds_read2_b32 v[162:163], v152 offset0:82 offset1:115
	s_waitcnt lgkmcnt(0)
	v_cvt_pk_bf16_f32 v161, v162, v163
	ds_read2_b32 v[162:163], v152 offset0:148 offset1:181
	s_waitcnt lgkmcnt(0)
	v_cvt_pk_bf16_f32 v162, v162, v163
	ds_read2_b32 v[164:165], v152 offset0:214 offset1:247
	s_waitcnt lgkmcnt(0)
	v_cvt_pk_bf16_f32 v163, v164, v165
	v_mad_i64_i32 v[164:165], s[76:77], s43, v4, 0
	v_lshl_add_u64 v[164:165], v[164:165], 1, v[2:3]
	global_store_dwordx4 v[164:165], v[160:163], off
	ds_read2_b32 v[160:161], v152 offset0:24 offset1:57
	v_or_b32_e32 v4, s74, v133
	s_waitcnt lgkmcnt(0)
	v_cvt_pk_bf16_f32 v160, v160, v161
	ds_read2_b32 v[162:163], v152 offset0:90 offset1:123
	s_waitcnt lgkmcnt(0)
	v_cvt_pk_bf16_f32 v161, v162, v163
	ds_read2_b32 v[162:163], v152 offset0:156 offset1:189
	s_waitcnt lgkmcnt(0)
	v_cvt_pk_bf16_f32 v162, v162, v163
	ds_read2_b32 v[164:165], v152 offset0:222 offset1:255
	s_waitcnt lgkmcnt(0)
	v_cvt_pk_bf16_f32 v163, v164, v165
	v_mad_i64_i32 v[164:165], s[74:75], s43, v4, 0
	v_lshl_add_u64 v[2:3], v[164:165], 1, v[2:3]
	global_store_dwordx4 v[2:3], v[160:163], off
	s_waitcnt lgkmcnt(0)
	s_add_i32 s33, s33, s35
; __device__ __forceinline__ void conv_load(const float* cWg, const float* cWu, const float* cWd, bf16* cWGU, bf16* cWD, int it, float (&v)[32], int lane) {
;     const ConvItem c = conv_decode(cWg, cWu, cWd, cWGU, cWD, it);
; #pragma unroll
;     for (int i = 0; i < 32; ++i) { const int kk = 2 * i + (lane >> 5); v[i] = c.W[(size_t)(c.k0 + kk) * c.N + c.n0 + (lane & 31)]; }
; }
; __device__ __forceinline__ void scan_quarter(LAS unsigned char* lds, const ScanConst& C, int m0, int T, int h, int quarter, const float* shift_prev  , const float* S0p  , float* Sout, const float* cWg, const float* cWu, const float* cWd, bf16* cWGU, bf16* cWD, int& conv_next, int conv_stride, int wa ...
;     ...
;             if (conv_next < FFN_ITEMS) { conv_load(cWg, cWu, cWd, cWGU, cWD, conv_next, cv, lane); conv_pending = true; }
.Lconv_no_finish:
	s_mov_b32 s98, 0
	s_cmpk_gt_i32 s33, 0x407f
	s_mov_b64 s[74:75], 0
	s_cbranch_scc1 .LBB0_816
	s_cmpk_gt_u32 s18, 0x7b
	s_cbranch_scc1 .LBB0_816
	s_add_i32 s10, s33, 0xffffea80
	s_cmpk_lt_i32 s33, 0x2b00
	s_cselect_b32 s30, 0x1580, s94
	s_cmpk_lt_u32 s10, 0x1580
	s_cselect_b32 s10, s10, s33
	s_cselect_b32 s11, s15, s13
	s_cselect_b32 s31, s14, s12
	s_cmpk_lt_i32 s33, 0x2b00
	s_cselect_b32 s31, s31, s48
	s_cselect_b32 s11, s11, s49
	s_add_i32 s43, s33, 0xffffd500
	s_cmpk_lt_i32 s33, 0x2b00
	s_cselect_b32 s74, 0xac, 64
	v_cvt_f32_ubyte0_e32 v2, s74
	v_rcp_iflag_f32_e32 v2, v2
	s_cselect_b32 s10, s10, s43
	s_sub_i32 s76, 0, s74
	s_abs_i32 s75, s10
	v_mul_f32_e32 v2, 0x4f7ffffe, v2
	v_cvt_u32_f32_e32 v2, v2
	s_ashr_i32 s43, s10, 31
	v_mov_b32_e32 v115, v5
	v_readfirstlane_b32 s77, v2
	s_mul_i32 s76, s76, s77
	s_mul_hi_u32 s76, s77, s76
	s_add_i32 s77, s77, s76
	s_mul_hi_u32 s76, s75, s77
	s_mul_i32 s77, s76, s74
	s_sub_i32 s75, s75, s77
	s_add_i32 s77, s76, 1
	s_sub_i32 vcc_lo, s75, s74
	s_cmp_ge_u32 s75, s74
	s_cselect_b32 s76, s77, s76
	s_cselect_b32 s75, vcc_lo, s75
	s_add_i32 s77, s76, 1
	s_cmp_ge_u32 s75, s74
	s_cselect_b32 s75, s77, s76
	s_xor_b32 s75, s75, s43
	s_sub_i32 s43, s75, s43
	s_mul_i32 s74, s43, s74
	s_sub_i32 s10, s10, s74
	s_lshl_b32 s74, s10, 5
	s_ashr_i32 s75, s74, 31
	s_lshl_b64 s[74:75], s[74:75], 2
	s_add_u32 s74, s31, s74
	v_lshl_or_b32 v4, s43, 6, v130
	s_addc_u32 s75, s11, s75
	v_lshl_add_u64 v[2:3], s[74:75], 0, v[114:115]
	v_mad_i64_i32 v[6:7], s[74:75], s30, v4, 0
	v_lshl_add_u64 v[6:7], v[6:7], 2, v[2:3]
	global_load_dword v6, v[6:7], off
	v_or_b32_e32 v7, 2, v4
	v_mad_i64_i32 v[8:9], s[74:75], s30, v7, 0
	v_lshl_add_u64 v[8:9], v[8:9], 2, v[2:3]
	global_load_dword v7, v[8:9], off
	v_or_b32_e32 v8, 4, v4
	v_mad_i64_i32 v[8:9], s[74:75], s30, v8, 0
	v_lshl_add_u64 v[8:9], v[8:9], 2, v[2:3]
	global_load_dword v8, v[8:9], off
	v_or_b32_e32 v9, 6, v4
	v_mad_i64_i32 v[10:11], s[74:75], s30, v9, 0
	v_lshl_add_u64 v[10:11], v[10:11], 2, v[2:3]
	global_load_dword v9, v[10:11], off
	v_or_b32_e32 v10, 8, v4
	v_mad_i64_i32 v[10:11], s[74:75], s30, v10, 0
	v_lshl_add_u64 v[10:11], v[10:11], 2, v[2:3]
	global_load_dword v10, v[10:11], off
	v_or_b32_e32 v11, 10, v4
	v_mad_i64_i32 v[12:13], s[74:75], s30, v11, 0
	v_lshl_add_u64 v[12:13], v[12:13], 2, v[2:3]
	global_load_dword v11, v[12:13], off
	v_or_b32_e32 v12, 12, v4
	v_mad_i64_i32 v[12:13], s[74:75], s30, v12, 0
	v_lshl_add_u64 v[12:13], v[12:13], 2, v[2:3]
	global_load_dword v12, v[12:13], off
	v_or_b32_e32 v13, 14, v4
	v_mad_i64_i32 v[14:15], s[74:75], s30, v13, 0
	v_lshl_add_u64 v[14:15], v[14:15], 2, v[2:3]
	global_load_dword v13, v[14:15], off
	v_or_b32_e32 v14, 16, v4
	v_mad_i64_i32 v[14:15], s[74:75], s30, v14, 0
	v_lshl_add_u64 v[14:15], v[14:15], 2, v[2:3]
	global_load_dword v14, v[14:15], off
	v_or_b32_e32 v15, 18, v4
	v_mad_i64_i32 v[16:17], s[74:75], s30, v15, 0
	v_lshl_add_u64 v[16:17], v[16:17], 2, v[2:3]
	global_load_dword v15, v[16:17], off
	v_or_b32_e32 v16, 20, v4
	v_mad_i64_i32 v[16:17], s[74:75], s30, v16, 0
	v_lshl_add_u64 v[16:17], v[16:17], 2, v[2:3]
	global_load_dword v16, v[16:17], off
	v_or_b32_e32 v17, 22, v4
	v_mad_i64_i32 v[18:19], s[74:75], s30, v17, 0
	v_lshl_add_u64 v[18:19], v[18:19], 2, v[2:3]
	global_load_dword v17, v[18:19], off
	v_or_b32_e32 v18, 24, v4
	v_mad_i64_i32 v[18:19], s[74:75], s30, v18, 0
	v_lshl_add_u64 v[18:19], v[18:19], 2, v[2:3]
	global_load_dword v18, v[18:19], off
	v_or_b32_e32 v19, 26, v4
	v_mad_i64_i32 v[20:21], s[74:75], s30, v19, 0
	v_lshl_add_u64 v[20:21], v[20:21], 2, v[2:3]
	global_load_dword v19, v[20:21], off
	v_or_b32_e32 v20, 28, v4
	v_mad_i64_i32 v[20:21], s[74:75], s30, v20, 0
	v_lshl_add_u64 v[20:21], v[20:21], 2, v[2:3]
	global_load_dword v20, v[20:21], off
	v_or_b32_e32 v21, 30, v4
	v_mad_i64_i32 v[22:23], s[74:75], s30, v21, 0
	v_lshl_add_u64 v[22:23], v[22:23], 2, v[2:3]
	global_load_dword v21, v[22:23], off
	v_or_b32_e32 v22, 32, v4
	v_mad_i64_i32 v[22:23], s[74:75], s30, v22, 0
	v_lshl_add_u64 v[22:23], v[22:23], 2, v[2:3]
	global_load_dword v22, v[22:23], off
	v_or_b32_e32 v23, 34, v4
	v_mad_i64_i32 v[24:25], s[74:75], s30, v23, 0
	v_lshl_add_u64 v[24:25], v[24:25], 2, v[2:3]
	global_load_dword v23, v[24:25], off
	v_or_b32_e32 v24, 36, v4
	v_mad_i64_i32 v[24:25], s[74:75], s30, v24, 0
	v_lshl_add_u64 v[24:25], v[24:25], 2, v[2:3]
	global_load_dword v24, v[24:25], off
	v_or_b32_e32 v25, 38, v4
	v_mad_i64_i32 v[26:27], s[74:75], s30, v25, 0
	v_lshl_add_u64 v[26:27], v[26:27], 2, v[2:3]
	global_load_dword v25, v[26:27], off
	v_or_b32_e32 v26, 40, v4
	v_mad_i64_i32 v[26:27], s[74:75], s30, v26, 0
	v_lshl_add_u64 v[26:27], v[26:27], 2, v[2:3]
	global_load_dword v26, v[26:27], off
	v_or_b32_e32 v27, 42, v4
	v_mad_i64_i32 v[28:29], s[74:75], s30, v27, 0
	v_lshl_add_u64 v[28:29], v[28:29], 2, v[2:3]
	global_load_dword v27, v[28:29], off
	v_or_b32_e32 v28, 44, v4
	v_mad_i64_i32 v[28:29], s[74:75], s30, v28, 0
	v_lshl_add_u64 v[28:29], v[28:29], 2, v[2:3]
	global_load_dword v28, v[28:29], off
	v_or_b32_e32 v29, 46, v4
	v_mad_i64_i32 v[30:31], s[74:75], s30, v29, 0
	v_lshl_add_u64 v[30:31], v[30:31], 2, v[2:3]
	global_load_dword v29, v[30:31], off
	v_or_b32_e32 v30, 48, v4
	v_mad_i64_i32 v[30:31], s[74:75], s30, v30, 0
	v_lshl_add_u64 v[30:31], v[30:31], 2, v[2:3]
	global_load_dword v30, v[30:31], off
	v_or_b32_e32 v31, 50, v4
	v_mad_i64_i32 v[32:33], s[74:75], s30, v31, 0
	v_lshl_add_u64 v[32:33], v[32:33], 2, v[2:3]
	global_load_dword v31, v[32:33], off
	v_or_b32_e32 v32, 52, v4
	v_mad_i64_i32 v[32:33], s[74:75], s30, v32, 0
	v_lshl_add_u64 v[32:33], v[32:33], 2, v[2:3]
	global_load_dword v32, v[32:33], off
	v_or_b32_e32 v33, 54, v4
	v_mad_i64_i32 v[34:35], s[74:75], s30, v33, 0
	v_lshl_add_u64 v[34:35], v[34:35], 2, v[2:3]
	global_load_dword v33, v[34:35], off
	v_or_b32_e32 v34, 56, v4
	v_mad_i64_i32 v[34:35], s[74:75], s30, v34, 0
	v_lshl_add_u64 v[34:35], v[34:35], 2, v[2:3]
	global_load_dword v34, v[34:35], off
	v_or_b32_e32 v35, 58, v4
	v_mad_i64_i32 v[36:37], s[74:75], s30, v35, 0
	v_lshl_add_u64 v[36:37], v[36:37], 2, v[2:3]
	global_load_dword v35, v[36:37], off
	v_or_b32_e32 v36, 60, v4
	v_or_b32_e32 v4, 62, v4
	v_mad_i64_i32 v[36:37], s[74:75], s30, v36, 0
	v_mad_i64_i32 v[160:161], s[30:31], s30, v4, 0
	v_lshl_add_u64 v[36:37], v[36:37], 2, v[2:3]
	v_lshl_add_u64 v[2:3], v[160:161], 2, v[2:3]
	global_load_dword v36, v[36:37], off
	global_load_dword v37, v[2:3], off
	s_mov_b64 s[74:75], -1
	s_mov_b32 s98, 1
	s_branch .LBB0_816
.Lconv_keep_pending:
	s_mov_b32 s98, 0
	s_mov_b64 s[74:75], -1
	s_branch .LBB0_816

; __device__ __forceinline__ KArgs* get_args() { KArgs* p = (KArgs*)__builtin_amdgcn_kernarg_segment_ptr(); asm volatile("" : "+s"(p)); return p; }
; __global__ void __launch_bounds__(NTHREADS, 2) fwd_kernel(Args args) {
	.amdhsa_kernel _Z10fwd_kernel4Args
		.amdhsa_group_segment_fixed_size 0
		.amdhsa_private_segment_fixed_size 0
		.amdhsa_kernarg_size 528
		.amdhsa_user_sgpr_count 2
		.amdhsa_user_sgpr_dispatch_ptr 0
		.amdhsa_user_sgpr_queue_ptr 0
		.amdhsa_user_sgpr_kernarg_segment_ptr 1
		.amdhsa_user_sgpr_dispatch_id 0
		.amdhsa_user_sgpr_kernarg_preload_length 0
		.amdhsa_user_sgpr_kernarg_preload_offset 0
		.amdhsa_user_sgpr_private_segment_size 0
		.amdhsa_uses_dynamic_stack 0
		.amdhsa_enable_private_segment 0
		.amdhsa_system_sgpr_workgroup_id_x 1
		.amdhsa_system_sgpr_workgroup_id_y 0
		.amdhsa_system_sgpr_workgroup_id_z 0
		.amdhsa_system_sgpr_workgroup_info 0
		.amdhsa_system_vgpr_workitem_id 2
		.amdhsa_next_free_vgpr 233
		.amdhsa_next_free_sgpr 100
		.amdhsa_accum_offset 236
		.amdhsa_reserve_vcc 1
		.amdhsa_float_round_mode_32 0
		.amdhsa_float_round_mode_16_64 0
		.amdhsa_float_denorm_mode_32 3
		.amdhsa_float_denorm_mode_16_64 3
		.amdhsa_dx10_clamp 1
		.amdhsa_ieee_mode 1
		.amdhsa_fp16_overflow 0
		.amdhsa_tg_split 0
		.amdhsa_exception_fp_ieee_invalid_op 0
		.amdhsa_exception_fp_denorm_src 0
		.amdhsa_exception_fp_ieee_div_zero 0
		.amdhsa_exception_fp_ieee_overflow 0
		.amdhsa_exception_fp_ieee_underflow 0
		.amdhsa_exception_fp_ieee_inexact 0
		.amdhsa_exception_int_div_zero 0
	.end_amdhsa_kernel

; __device__ __forceinline__ KArgs* get_args() { KArgs* p = (KArgs*)__builtin_amdgcn_kernarg_segment_ptr(); asm volatile("" : "+s"(p)); return p; }
; __global__ void __launch_bounds__(NTHREADS, 2) fwd_kernel(Args args) {
amdhsa.kernels:
  - .agpr_count:     0
    .args:
      - .offset:         0
        .size:           272
        .value_kind:     by_value
      - .offset:         272
        .size:           4
        .value_kind:     hidden_block_count_x
      - .offset:         276
        .size:           4
        .value_kind:     hidden_block_count_y
      - .offset:         280
        .size:           4
        .value_kind:     hidden_block_count_z
      - .offset:         284
        .size:           2
        .value_kind:     hidden_group_size_x
      - .offset:         286
        .size:           2
        .value_kind:     hidden_group_size_y
      - .offset:         288
        .size:           2
        .value_kind:     hidden_group_size_z
      - .offset:         290
        .size:           2
        .value_kind:     hidden_remainder_x
      - .offset:         292
        .size:           2
        .value_kind:     hidden_remainder_y
      - .offset:         294
        .size:           2
        .value_kind:     hidden_remainder_z
      - .offset:         312
        .size:           8
        .value_kind:     hidden_global_offset_x
      - .offset:         320
        .size:           8
        .value_kind:     hidden_global_offset_y
      - .offset:         328
        .size:           8
        .value_kind:     hidden_global_offset_z
      - .offset:         336
        .size:           2
        .value_kind:     hidden_grid_dims
      - .offset:         360
        .size:           8
        .value_kind:     hidden_multigrid_sync_arg
      - .offset:         392
        .size:           4
        .value_kind:     hidden_dynamic_lds_size
    .group_segment_fixed_size: 0
    .kernarg_segment_align: 8
    .kernarg_segment_size: 528
    .language:       OpenCL C
    .language_version:
      - 2
      - 0
    .max_flat_workgroup_size: 512
    .name:           _Z10fwd_kernel4Args
    .private_segment_fixed_size: 0
    .sgpr_count:     106
    .sgpr_spill_count: 5
    .symbol:         _Z10fwd_kernel4Args.kd
    .uniform_work_group_size: 1
    .uses_dynamic_stack: false
    .vgpr_count:     233
    .vgpr_spill_count: 0
    .wavefront_size: 64
